# hand-written EpiFfnAct epilogue (P10 FFN-in GEMM): packed f32 math, DPP-folded conv3 taps, conv weights loaded once per unit; same math and dtypes
# speedup vs baseline: 1.0473x; 1.0347x over previous
.LBB0_1518:
	v_readlane_b32 s14, v255, 25
	v_readlane_b32 s15, v255, 26
	v_readlane_b32 s12, v255, 27
	v_readlane_b32 s13, v255, 28
	v_mbcnt_lo_u32_b32 v156, -1, 0
	v_mbcnt_hi_u32_b32 v156, -1, v156
	s_lshl_b32 s8, s4, 7
	s_or_b32 s8, s8, s70
	s_lshl_b32 s9, s6, 8
	s_add_i32 s9, s9, s69
	v_and_b32_e32 v157, 15, v156
	v_lshrrev_b32_e32 v158, 4, v156
	v_lshl_add_u32 v158, v158, 3, s8
	v_add_u32_e32 v159, s9, v157
	v_lshlrev_b32_e32 v160, 2, v159
	v_lshlrev_b32_e32 v161, 2, v158
	s_add_u32 s16, s14, 0x2c00
	s_addc_u32 s17, s15, 0
	s_add_u32 s18, s14, 0x5800
	s_addc_u32 s19, s15, 0
	global_load_dword v148, v160, s[44:45]
	global_load_dword v150, v160, s[44:45] offset:64
	global_load_dword v152, v160, s[44:45] offset:128
	global_load_dword v154, v160, s[44:45] offset:192
	global_load_dword v162, v160, s[44:45] offset:512
	global_load_dword v164, v160, s[44:45] offset:576
	global_load_dword v174, v160, s[44:45] offset:640
	global_load_dword v176, v160, s[44:45] offset:704
	global_load_dwordx4 v[182:185], v161, s[14:15]
	global_load_dwordx4 v[186:189], v161, s[14:15] offset:16
	global_load_dwordx4 v[190:193], v161, s[16:17]
	global_load_dwordx4 v[194:197], v161, s[16:17] offset:16
	global_load_dwordx4 v[198:201], v161, s[18:19]
	global_load_dwordx4 v[202:205], v161, s[18:19] offset:16
	global_load_dwordx4 v[206:209], v161, s[12:13]
	global_load_dwordx4 v[210:213], v161, s[12:13] offset:16
	v_mov_b32_e32 v142, 0xc0135761
	v_mov_b32_e32 v143, 0xc0135761
	v_mov_b32_e32 v144, 0xbdd2d3e8
	v_mov_b32_e32 v145, 0xbdd2d3e8
	v_mov_b32_e32 v146, 1.0
	v_mov_b32_e32 v147, 1.0
	v_mov_b32_e32 v163, 0x358637bd
	v_mul_u32_u24_e32 v225, 0x1600, v159
	v_lshl_add_u32 v225, v158, 1, v225
	v_add_u32_e32 v222, 2, v157
	v_and_b32_e32 v222, 15, v222
	s_lshl_b32 s22, s6, 2
	s_lshr_b32 s23, s69, 6
	s_add_i32 s22, s22, s23
	s_lshl_b32 s22, s22, 2
	s_waitcnt vmcnt(0)
	v_fmamk_f32 v148, v148, 0x3a800000, v163
	v_fmamk_f32 v150, v150, 0x3a800000, v163
	v_fmamk_f32 v152, v152, 0x3a800000, v163
	v_fmamk_f32 v154, v154, 0x3a800000, v163
	v_fmamk_f32 v162, v162, 0x3a800000, v163
	v_fmamk_f32 v164, v164, 0x3a800000, v163
	v_fmamk_f32 v174, v174, 0x3a800000, v163
	v_fmamk_f32 v176, v176, 0x3a800000, v163
	v_rsq_f32_e32 v148, v148
	v_rsq_f32_e32 v150, v150
	v_rsq_f32_e32 v152, v152
	v_rsq_f32_e32 v154, v154
	v_rsq_f32_e32 v162, v162
	v_rsq_f32_e32 v164, v164
	v_rsq_f32_e32 v174, v174
	v_rsq_f32_e32 v176, v176
	s_nop 0
	v_pk_mul_f32 v[124:125], v[124:125], v[148:149] op_sel_hi:[1,0]
	v_pk_mul_f32 v[126:127], v[126:127], v[148:149] op_sel_hi:[1,0]
	v_pk_mul_f32 v[100:101], v[100:101], v[148:149] op_sel_hi:[1,0]
	v_pk_mul_f32 v[102:103], v[102:103], v[148:149] op_sel_hi:[1,0]
	v_pk_mul_f32 v[120:121], v[120:121], v[148:149] op_sel_hi:[1,0]
	v_pk_mul_f32 v[122:123], v[122:123], v[148:149] op_sel_hi:[1,0]
	v_pk_mul_f32 v[88:89], v[88:89], v[148:149] op_sel_hi:[1,0]
	v_pk_mul_f32 v[90:91], v[90:91], v[148:149] op_sel_hi:[1,0]
	v_pk_mul_f32 v[108:109], v[108:109], v[150:151] op_sel_hi:[1,0]
	v_pk_mul_f32 v[110:111], v[110:111], v[150:151] op_sel_hi:[1,0]
	v_pk_mul_f32 v[84:85], v[84:85], v[150:151] op_sel_hi:[1,0]
	v_pk_mul_f32 v[86:87], v[86:87], v[150:151] op_sel_hi:[1,0]
	v_pk_mul_f32 v[96:97], v[96:97], v[150:151] op_sel_hi:[1,0]
	v_pk_mul_f32 v[98:99], v[98:99], v[150:151] op_sel_hi:[1,0]
	v_pk_mul_f32 v[76:77], v[76:77], v[150:151] op_sel_hi:[1,0]
	v_pk_mul_f32 v[78:79], v[78:79], v[150:151] op_sel_hi:[1,0]
	v_pk_mul_f32 v[104:105], v[104:105], v[152:153] op_sel_hi:[1,0]
	v_pk_mul_f32 v[106:107], v[106:107], v[152:153] op_sel_hi:[1,0]
	v_pk_mul_f32 v[80:81], v[80:81], v[152:153] op_sel_hi:[1,0]
	v_pk_mul_f32 v[82:83], v[82:83], v[152:153] op_sel_hi:[1,0]
	v_pk_mul_f32 v[92:93], v[92:93], v[152:153] op_sel_hi:[1,0]
	v_pk_mul_f32 v[94:95], v[94:95], v[152:153] op_sel_hi:[1,0]
	v_pk_mul_f32 v[68:69], v[68:69], v[152:153] op_sel_hi:[1,0]
	v_pk_mul_f32 v[70:71], v[70:71], v[152:153] op_sel_hi:[1,0]
	v_pk_mul_f32 v[116:117], v[116:117], v[154:155] op_sel_hi:[1,0]
	v_pk_mul_f32 v[118:119], v[118:119], v[154:155] op_sel_hi:[1,0]
	v_pk_mul_f32 v[72:73], v[72:73], v[154:155] op_sel_hi:[1,0]
	v_pk_mul_f32 v[74:75], v[74:75], v[154:155] op_sel_hi:[1,0]
	v_pk_mul_f32 v[112:113], v[112:113], v[154:155] op_sel_hi:[1,0]
	v_pk_mul_f32 v[114:115], v[114:115], v[154:155] op_sel_hi:[1,0]
	v_pk_mul_f32 v[64:65], v[64:65], v[154:155] op_sel_hi:[1,0]
	v_pk_mul_f32 v[66:67], v[66:67], v[154:155] op_sel_hi:[1,0]
	v_cmp_gt_u32_e32 vcc, 2, v157
	v_cvt_pk_bf16_f32 v214, v124, v125
	v_cvt_pk_bf16_f32 v215, v126, v127
	v_cvt_pk_bf16_f32 v216, v120, v121
	v_cvt_pk_bf16_f32 v217, v122, v123
	v_cvt_pk_bf16_f32 v218, v116, v117
	v_cvt_pk_bf16_f32 v219, v118, v119
	v_cvt_pk_bf16_f32 v220, v112, v113
	v_cvt_pk_bf16_f32 v221, v114, v115
	v_cndmask_b32_e32 v214, v218, v214, vcc
	v_cndmask_b32_e32 v215, v219, v215, vcc
	v_cndmask_b32_e32 v216, v220, v216, vcc
	v_cndmask_b32_e32 v217, v221, v217, vcc
	v_and_b32_e32 v223, 3, v222
	v_add_u32_e32 v223, s22, v223
	v_mul_u32_u24_e32 v223, 0x1600, v223
	v_lshl_add_u32 v224, v158, 1, v223
	v_cmp_gt_u32_e64 s[10:11], 4, v222
	s_and_saveexec_b64 s[20:21], s[10:11]
	global_store_dwordx4 v224, v[214:217], s[48:49]
	s_mov_b64 exec, s[20:21]
	s_nop 4
	v_pk_fma_f32 v[226:227], v[116:117], v[198:199], v[206:207]
	v_pk_fma_f32 v[230:231], v[112:113], v[202:203], v[210:211]
	v_pk_fma_f32 v[228:229], v[118:119], v[200:201], v[208:209]
	v_pk_fma_f32 v[232:233], v[114:115], v[204:205], v[212:213]
	v_fmac_f32_dpp v226, v116, v190 row_shr:1 row_mask:0xf bank_mask:0xf
	v_fmac_f32_dpp v230, v112, v194 row_shr:1 row_mask:0xf bank_mask:0xf
	v_fmac_f32_dpp v226, v104, v190 row_shl:15 row_mask:0xf bank_mask:0xf
	v_fmac_f32_dpp v230, v92, v194 row_shl:15 row_mask:0xf bank_mask:0xf
	v_fmac_f32_dpp v226, v116, v182 row_shr:2 row_mask:0xf bank_mask:0xf
	v_fmac_f32_dpp v230, v112, v186 row_shr:2 row_mask:0xf bank_mask:0xf
	v_fmac_f32_dpp v226, v104, v182 row_shl:14 row_mask:0xf bank_mask:0xf
	v_fmac_f32_dpp v230, v92, v186 row_shl:14 row_mask:0xf bank_mask:0xf
	v_fmac_f32_dpp v227, v117, v191 row_shr:1 row_mask:0xf bank_mask:0xf
	v_fmac_f32_dpp v231, v113, v195 row_shr:1 row_mask:0xf bank_mask:0xf
	v_fmac_f32_dpp v227, v105, v191 row_shl:15 row_mask:0xf bank_mask:0xf
	v_fmac_f32_dpp v231, v93, v195 row_shl:15 row_mask:0xf bank_mask:0xf
	v_fmac_f32_dpp v227, v117, v183 row_shr:2 row_mask:0xf bank_mask:0xf
	v_fmac_f32_dpp v231, v113, v187 row_shr:2 row_mask:0xf bank_mask:0xf
	v_fmac_f32_dpp v227, v105, v183 row_shl:14 row_mask:0xf bank_mask:0xf
	v_fmac_f32_dpp v231, v93, v187 row_shl:14 row_mask:0xf bank_mask:0xf
	v_fmac_f32_dpp v228, v118, v192 row_shr:1 row_mask:0xf bank_mask:0xf
	v_fmac_f32_dpp v232, v114, v196 row_shr:1 row_mask:0xf bank_mask:0xf
	v_fmac_f32_dpp v228, v106, v192 row_shl:15 row_mask:0xf bank_mask:0xf
	v_fmac_f32_dpp v232, v94, v196 row_shl:15 row_mask:0xf bank_mask:0xf
	v_fmac_f32_dpp v228, v118, v184 row_shr:2 row_mask:0xf bank_mask:0xf
	v_fmac_f32_dpp v232, v114, v188 row_shr:2 row_mask:0xf bank_mask:0xf
	v_fmac_f32_dpp v228, v106, v184 row_shl:14 row_mask:0xf bank_mask:0xf
	v_fmac_f32_dpp v232, v94, v188 row_shl:14 row_mask:0xf bank_mask:0xf
	v_fmac_f32_dpp v229, v119, v193 row_shr:1 row_mask:0xf bank_mask:0xf
	v_fmac_f32_dpp v233, v115, v197 row_shr:1 row_mask:0xf bank_mask:0xf
	v_fmac_f32_dpp v229, v107, v193 row_shl:15 row_mask:0xf bank_mask:0xf
	v_fmac_f32_dpp v233, v95, v197 row_shl:15 row_mask:0xf bank_mask:0xf
	v_fmac_f32_dpp v229, v119, v185 row_shr:2 row_mask:0xf bank_mask:0xf
	v_fmac_f32_dpp v233, v115, v189 row_shr:2 row_mask:0xf bank_mask:0xf
	v_fmac_f32_dpp v229, v107, v185 row_shl:14 row_mask:0xf bank_mask:0xf
	v_fmac_f32_dpp v233, v95, v189 row_shl:14 row_mask:0xf bank_mask:0xf
	v_pk_mul_f32 v[234:235], v[226:227], v[226:227]
	v_pk_mul_f32 v[238:239], v[230:231], v[230:231]
	v_pk_mul_f32 v[236:237], v[228:229], v[228:229]
	v_pk_mul_f32 v[240:241], v[232:233], v[232:233]
	v_pk_fma_f32 v[234:235], v[234:235], v[144:145], v[142:143]
	v_pk_fma_f32 v[238:239], v[238:239], v[144:145], v[142:143]
	v_pk_fma_f32 v[236:237], v[236:237], v[144:145], v[142:143]
	v_pk_fma_f32 v[240:241], v[240:241], v[144:145], v[142:143]
	v_pk_mul_f32 v[234:235], v[234:235], v[226:227]
	v_pk_mul_f32 v[238:239], v[238:239], v[230:231]
	v_pk_mul_f32 v[236:237], v[236:237], v[228:229]
	v_pk_mul_f32 v[240:241], v[240:241], v[232:233]
	v_exp_f32_e32 v234, v234
	v_exp_f32_e32 v238, v238
	v_exp_f32_e32 v235, v235
	v_exp_f32_e32 v239, v239
	v_exp_f32_e32 v236, v236
	v_exp_f32_e32 v240, v240
	v_exp_f32_e32 v237, v237
	v_exp_f32_e32 v241, v241
	s_nop 0
	s_nop 0
	v_pk_add_f32 v[234:235], v[234:235], v[146:147]
	v_pk_add_f32 v[238:239], v[238:239], v[146:147]
	v_pk_add_f32 v[236:237], v[236:237], v[146:147]
	v_pk_add_f32 v[240:241], v[240:241], v[146:147]
	v_rcp_f32_e32 v234, v234
	v_rcp_f32_e32 v238, v238
	v_rcp_f32_e32 v235, v235
	v_rcp_f32_e32 v239, v239
	v_rcp_f32_e32 v236, v236
	v_rcp_f32_e32 v240, v240
	v_rcp_f32_e32 v237, v237
	v_rcp_f32_e32 v241, v241
	s_nop 0
	s_nop 0
	v_pk_mul_f32 v[234:235], v[234:235], v[226:227]
	v_pk_mul_f32 v[238:239], v[238:239], v[230:231]
	v_pk_mul_f32 v[236:237], v[236:237], v[228:229]
	v_pk_mul_f32 v[240:241], v[240:241], v[232:233]
	v_pk_mul_f32 v[72:73], v[72:73], v[234:235]
	v_pk_mul_f32 v[64:65], v[64:65], v[238:239]
	v_pk_mul_f32 v[74:75], v[74:75], v[236:237]
	v_pk_mul_f32 v[66:67], v[66:67], v[240:241]
	v_cvt_pk_bf16_f32 v72, v72, v73
	v_cvt_pk_bf16_f32 v73, v74, v75
	v_cvt_pk_bf16_f32 v74, v64, v65
	v_cvt_pk_bf16_f32 v75, v66, v67
	v_add_u32_e32 v245, 0x42000, v225
	global_store_dwordx4 v245, v[72:75], s[46:47]
	v_pk_fma_f32 v[226:227], v[104:105], v[198:199], v[206:207]
	v_pk_fma_f32 v[230:231], v[92:93], v[202:203], v[210:211]
	v_pk_fma_f32 v[228:229], v[106:107], v[200:201], v[208:209]
	v_pk_fma_f32 v[232:233], v[94:95], v[204:205], v[212:213]
	v_fmac_f32_dpp v226, v104, v190 row_shr:1 row_mask:0xf bank_mask:0xf
	v_fmac_f32_dpp v230, v92, v194 row_shr:1 row_mask:0xf bank_mask:0xf
	v_fmac_f32_dpp v226, v108, v190 row_shl:15 row_mask:0xf bank_mask:0xf
	v_fmac_f32_dpp v230, v96, v194 row_shl:15 row_mask:0xf bank_mask:0xf
	v_fmac_f32_dpp v226, v104, v182 row_shr:2 row_mask:0xf bank_mask:0xf
	v_fmac_f32_dpp v230, v92, v186 row_shr:2 row_mask:0xf bank_mask:0xf
	v_fmac_f32_dpp v226, v108, v182 row_shl:14 row_mask:0xf bank_mask:0xf
	v_fmac_f32_dpp v230, v96, v186 row_shl:14 row_mask:0xf bank_mask:0xf
	v_fmac_f32_dpp v227, v105, v191 row_shr:1 row_mask:0xf bank_mask:0xf
	v_fmac_f32_dpp v231, v93, v195 row_shr:1 row_mask:0xf bank_mask:0xf
	v_fmac_f32_dpp v227, v109, v191 row_shl:15 row_mask:0xf bank_mask:0xf
	v_fmac_f32_dpp v231, v97, v195 row_shl:15 row_mask:0xf bank_mask:0xf
	v_fmac_f32_dpp v227, v105, v183 row_shr:2 row_mask:0xf bank_mask:0xf
	v_fmac_f32_dpp v231, v93, v187 row_shr:2 row_mask:0xf bank_mask:0xf
	v_fmac_f32_dpp v227, v109, v183 row_shl:14 row_mask:0xf bank_mask:0xf
	v_fmac_f32_dpp v231, v97, v187 row_shl:14 row_mask:0xf bank_mask:0xf
	v_fmac_f32_dpp v228, v106, v192 row_shr:1 row_mask:0xf bank_mask:0xf
	v_fmac_f32_dpp v232, v94, v196 row_shr:1 row_mask:0xf bank_mask:0xf
	v_fmac_f32_dpp v228, v110, v192 row_shl:15 row_mask:0xf bank_mask:0xf
	v_fmac_f32_dpp v232, v98, v196 row_shl:15 row_mask:0xf bank_mask:0xf
	v_fmac_f32_dpp v228, v106, v184 row_shr:2 row_mask:0xf bank_mask:0xf
	v_fmac_f32_dpp v232, v94, v188 row_shr:2 row_mask:0xf bank_mask:0xf
	v_fmac_f32_dpp v228, v110, v184 row_shl:14 row_mask:0xf bank_mask:0xf
	v_fmac_f32_dpp v232, v98, v188 row_shl:14 row_mask:0xf bank_mask:0xf
	v_fmac_f32_dpp v229, v107, v193 row_shr:1 row_mask:0xf bank_mask:0xf
	v_fmac_f32_dpp v233, v95, v197 row_shr:1 row_mask:0xf bank_mask:0xf
	v_fmac_f32_dpp v229, v111, v193 row_shl:15 row_mask:0xf bank_mask:0xf
	v_fmac_f32_dpp v233, v99, v197 row_shl:15 row_mask:0xf bank_mask:0xf
	v_fmac_f32_dpp v229, v107, v185 row_shr:2 row_mask:0xf bank_mask:0xf
	v_fmac_f32_dpp v233, v95, v189 row_shr:2 row_mask:0xf bank_mask:0xf
	v_fmac_f32_dpp v229, v111, v185 row_shl:14 row_mask:0xf bank_mask:0xf
	v_fmac_f32_dpp v233, v99, v189 row_shl:14 row_mask:0xf bank_mask:0xf
	v_pk_mul_f32 v[234:235], v[226:227], v[226:227]
	v_pk_mul_f32 v[238:239], v[230:231], v[230:231]
	v_pk_mul_f32 v[236:237], v[228:229], v[228:229]
	v_pk_mul_f32 v[240:241], v[232:233], v[232:233]
	v_pk_fma_f32 v[234:235], v[234:235], v[144:145], v[142:143]
	v_pk_fma_f32 v[238:239], v[238:239], v[144:145], v[142:143]
	v_pk_fma_f32 v[236:237], v[236:237], v[144:145], v[142:143]
	v_pk_fma_f32 v[240:241], v[240:241], v[144:145], v[142:143]
	v_pk_mul_f32 v[234:235], v[234:235], v[226:227]
	v_pk_mul_f32 v[238:239], v[238:239], v[230:231]
	v_pk_mul_f32 v[236:237], v[236:237], v[228:229]
	v_pk_mul_f32 v[240:241], v[240:241], v[232:233]
	v_exp_f32_e32 v234, v234
	v_exp_f32_e32 v238, v238
	v_exp_f32_e32 v235, v235
	v_exp_f32_e32 v239, v239
	v_exp_f32_e32 v236, v236
	v_exp_f32_e32 v240, v240
	v_exp_f32_e32 v237, v237
	v_exp_f32_e32 v241, v241
	s_nop 0
	s_nop 0
	v_pk_add_f32 v[234:235], v[234:235], v[146:147]
	v_pk_add_f32 v[238:239], v[238:239], v[146:147]
	v_pk_add_f32 v[236:237], v[236:237], v[146:147]
	v_pk_add_f32 v[240:241], v[240:241], v[146:147]
	v_rcp_f32_e32 v234, v234
	v_rcp_f32_e32 v238, v238
	v_rcp_f32_e32 v235, v235
	v_rcp_f32_e32 v239, v239
	v_rcp_f32_e32 v236, v236
	v_rcp_f32_e32 v240, v240
	v_rcp_f32_e32 v237, v237
	v_rcp_f32_e32 v241, v241
	s_nop 0
	s_nop 0
	v_pk_mul_f32 v[234:235], v[234:235], v[226:227]
	v_pk_mul_f32 v[238:239], v[238:239], v[230:231]
	v_pk_mul_f32 v[236:237], v[236:237], v[228:229]
	v_pk_mul_f32 v[240:241], v[240:241], v[232:233]
	v_pk_mul_f32 v[80:81], v[80:81], v[234:235]
	v_pk_mul_f32 v[68:69], v[68:69], v[238:239]
	v_pk_mul_f32 v[82:83], v[82:83], v[236:237]
	v_pk_mul_f32 v[70:71], v[70:71], v[240:241]
	v_cvt_pk_bf16_f32 v80, v80, v81
	v_cvt_pk_bf16_f32 v81, v82, v83
	v_cvt_pk_bf16_f32 v82, v68, v69
	v_cvt_pk_bf16_f32 v83, v70, v71
	v_add_u32_e32 v244, 0x2c000, v225
	global_store_dwordx4 v244, v[80:83], s[46:47]
	v_pk_fma_f32 v[226:227], v[108:109], v[198:199], v[206:207]
	v_pk_fma_f32 v[230:231], v[96:97], v[202:203], v[210:211]
	v_pk_fma_f32 v[228:229], v[110:111], v[200:201], v[208:209]
	v_pk_fma_f32 v[232:233], v[98:99], v[204:205], v[212:213]
	v_fmac_f32_dpp v226, v108, v190 row_shr:1 row_mask:0xf bank_mask:0xf
	v_fmac_f32_dpp v230, v96, v194 row_shr:1 row_mask:0xf bank_mask:0xf
	v_fmac_f32_dpp v226, v124, v190 row_shl:15 row_mask:0xf bank_mask:0xf
	v_fmac_f32_dpp v230, v120, v194 row_shl:15 row_mask:0xf bank_mask:0xf
	v_fmac_f32_dpp v226, v108, v182 row_shr:2 row_mask:0xf bank_mask:0xf
	v_fmac_f32_dpp v230, v96, v186 row_shr:2 row_mask:0xf bank_mask:0xf
	v_fmac_f32_dpp v226, v124, v182 row_shl:14 row_mask:0xf bank_mask:0xf
	v_fmac_f32_dpp v230, v120, v186 row_shl:14 row_mask:0xf bank_mask:0xf
	v_fmac_f32_dpp v227, v109, v191 row_shr:1 row_mask:0xf bank_mask:0xf
	v_fmac_f32_dpp v231, v97, v195 row_shr:1 row_mask:0xf bank_mask:0xf
	v_fmac_f32_dpp v227, v125, v191 row_shl:15 row_mask:0xf bank_mask:0xf
	v_fmac_f32_dpp v231, v121, v195 row_shl:15 row_mask:0xf bank_mask:0xf
	v_fmac_f32_dpp v227, v109, v183 row_shr:2 row_mask:0xf bank_mask:0xf
	v_fmac_f32_dpp v231, v97, v187 row_shr:2 row_mask:0xf bank_mask:0xf
	v_fmac_f32_dpp v227, v125, v183 row_shl:14 row_mask:0xf bank_mask:0xf
	v_fmac_f32_dpp v231, v121, v187 row_shl:14 row_mask:0xf bank_mask:0xf
	v_fmac_f32_dpp v228, v110, v192 row_shr:1 row_mask:0xf bank_mask:0xf
	v_fmac_f32_dpp v232, v98, v196 row_shr:1 row_mask:0xf bank_mask:0xf
	v_fmac_f32_dpp v228, v126, v192 row_shl:15 row_mask:0xf bank_mask:0xf
	v_fmac_f32_dpp v232, v122, v196 row_shl:15 row_mask:0xf bank_mask:0xf
	v_fmac_f32_dpp v228, v110, v184 row_shr:2 row_mask:0xf bank_mask:0xf
	v_fmac_f32_dpp v232, v98, v188 row_shr:2 row_mask:0xf bank_mask:0xf
	v_fmac_f32_dpp v228, v126, v184 row_shl:14 row_mask:0xf bank_mask:0xf
	v_fmac_f32_dpp v232, v122, v188 row_shl:14 row_mask:0xf bank_mask:0xf
	v_fmac_f32_dpp v229, v111, v193 row_shr:1 row_mask:0xf bank_mask:0xf
	v_fmac_f32_dpp v233, v99, v197 row_shr:1 row_mask:0xf bank_mask:0xf
	v_fmac_f32_dpp v229, v127, v193 row_shl:15 row_mask:0xf bank_mask:0xf
	v_fmac_f32_dpp v233, v123, v197 row_shl:15 row_mask:0xf bank_mask:0xf
	v_fmac_f32_dpp v229, v111, v185 row_shr:2 row_mask:0xf bank_mask:0xf
	v_fmac_f32_dpp v233, v99, v189 row_shr:2 row_mask:0xf bank_mask:0xf
	v_fmac_f32_dpp v229, v127, v185 row_shl:14 row_mask:0xf bank_mask:0xf
	v_fmac_f32_dpp v233, v123, v189 row_shl:14 row_mask:0xf bank_mask:0xf
	v_pk_mul_f32 v[234:235], v[226:227], v[226:227]
	v_pk_mul_f32 v[238:239], v[230:231], v[230:231]
	v_pk_mul_f32 v[236:237], v[228:229], v[228:229]
	v_pk_mul_f32 v[240:241], v[232:233], v[232:233]
	v_pk_fma_f32 v[234:235], v[234:235], v[144:145], v[142:143]
	v_pk_fma_f32 v[238:239], v[238:239], v[144:145], v[142:143]
	v_pk_fma_f32 v[236:237], v[236:237], v[144:145], v[142:143]
	v_pk_fma_f32 v[240:241], v[240:241], v[144:145], v[142:143]
	v_pk_mul_f32 v[234:235], v[234:235], v[226:227]
	v_pk_mul_f32 v[238:239], v[238:239], v[230:231]
	v_pk_mul_f32 v[236:237], v[236:237], v[228:229]
	v_pk_mul_f32 v[240:241], v[240:241], v[232:233]
	v_exp_f32_e32 v234, v234
	v_exp_f32_e32 v238, v238
	v_exp_f32_e32 v235, v235
	v_exp_f32_e32 v239, v239
	v_exp_f32_e32 v236, v236
	v_exp_f32_e32 v240, v240
	v_exp_f32_e32 v237, v237
	v_exp_f32_e32 v241, v241
	s_nop 0
	s_nop 0
	v_pk_add_f32 v[234:235], v[234:235], v[146:147]
	v_pk_add_f32 v[238:239], v[238:239], v[146:147]
	v_pk_add_f32 v[236:237], v[236:237], v[146:147]
	v_pk_add_f32 v[240:241], v[240:241], v[146:147]
	v_rcp_f32_e32 v234, v234
	v_rcp_f32_e32 v238, v238
	v_rcp_f32_e32 v235, v235
	v_rcp_f32_e32 v239, v239
	v_rcp_f32_e32 v236, v236
	v_rcp_f32_e32 v240, v240
	v_rcp_f32_e32 v237, v237
	v_rcp_f32_e32 v241, v241
	s_nop 0
	s_nop 0
	v_pk_mul_f32 v[234:235], v[234:235], v[226:227]
	v_pk_mul_f32 v[238:239], v[238:239], v[230:231]
	v_pk_mul_f32 v[236:237], v[236:237], v[228:229]
	v_pk_mul_f32 v[240:241], v[240:241], v[232:233]
	v_pk_mul_f32 v[84:85], v[84:85], v[234:235]
	v_pk_mul_f32 v[76:77], v[76:77], v[238:239]
	v_pk_mul_f32 v[86:87], v[86:87], v[236:237]
	v_pk_mul_f32 v[78:79], v[78:79], v[240:241]
	v_cvt_pk_bf16_f32 v84, v84, v85
	v_cvt_pk_bf16_f32 v85, v86, v87
	v_cvt_pk_bf16_f32 v86, v76, v77
	v_cvt_pk_bf16_f32 v87, v78, v79
	v_add_u32_e32 v243, 0x16000, v225
	global_store_dwordx4 v243, v[84:87], s[46:47]
	v_pk_fma_f32 v[226:227], v[124:125], v[198:199], v[206:207]
	v_pk_fma_f32 v[230:231], v[120:121], v[202:203], v[210:211]
	v_pk_fma_f32 v[228:229], v[126:127], v[200:201], v[208:209]
	v_pk_fma_f32 v[232:233], v[122:123], v[204:205], v[212:213]
	v_fmac_f32_dpp v226, v124, v190 row_shr:1 row_mask:0xf bank_mask:0xf
	v_fmac_f32_dpp v230, v120, v194 row_shr:1 row_mask:0xf bank_mask:0xf
	v_fmac_f32_dpp v226, v124, v182 row_shr:2 row_mask:0xf bank_mask:0xf
	v_fmac_f32_dpp v230, v120, v186 row_shr:2 row_mask:0xf bank_mask:0xf
	v_fmac_f32_dpp v227, v125, v191 row_shr:1 row_mask:0xf bank_mask:0xf
	v_fmac_f32_dpp v231, v121, v195 row_shr:1 row_mask:0xf bank_mask:0xf
	v_fmac_f32_dpp v227, v125, v183 row_shr:2 row_mask:0xf bank_mask:0xf
	v_fmac_f32_dpp v231, v121, v187 row_shr:2 row_mask:0xf bank_mask:0xf
	v_fmac_f32_dpp v228, v126, v192 row_shr:1 row_mask:0xf bank_mask:0xf
	v_fmac_f32_dpp v232, v122, v196 row_shr:1 row_mask:0xf bank_mask:0xf
	v_fmac_f32_dpp v228, v126, v184 row_shr:2 row_mask:0xf bank_mask:0xf
	v_fmac_f32_dpp v232, v122, v188 row_shr:2 row_mask:0xf bank_mask:0xf
	v_fmac_f32_dpp v229, v127, v193 row_shr:1 row_mask:0xf bank_mask:0xf
	v_fmac_f32_dpp v233, v123, v197 row_shr:1 row_mask:0xf bank_mask:0xf
	v_fmac_f32_dpp v229, v127, v185 row_shr:2 row_mask:0xf bank_mask:0xf
	v_fmac_f32_dpp v233, v123, v189 row_shr:2 row_mask:0xf bank_mask:0xf
	v_pk_mul_f32 v[234:235], v[226:227], v[226:227]
	v_pk_mul_f32 v[238:239], v[230:231], v[230:231]
	v_pk_mul_f32 v[236:237], v[228:229], v[228:229]
	v_pk_mul_f32 v[240:241], v[232:233], v[232:233]
	v_pk_fma_f32 v[234:235], v[234:235], v[144:145], v[142:143]
	v_pk_fma_f32 v[238:239], v[238:239], v[144:145], v[142:143]
	v_pk_fma_f32 v[236:237], v[236:237], v[144:145], v[142:143]
	v_pk_fma_f32 v[240:241], v[240:241], v[144:145], v[142:143]
	v_pk_mul_f32 v[234:235], v[234:235], v[226:227]
	v_pk_mul_f32 v[238:239], v[238:239], v[230:231]
	v_pk_mul_f32 v[236:237], v[236:237], v[228:229]
	v_pk_mul_f32 v[240:241], v[240:241], v[232:233]
	v_exp_f32_e32 v234, v234
	v_exp_f32_e32 v238, v238
	v_exp_f32_e32 v235, v235
	v_exp_f32_e32 v239, v239
	v_exp_f32_e32 v236, v236
	v_exp_f32_e32 v240, v240
	v_exp_f32_e32 v237, v237
	v_exp_f32_e32 v241, v241
	s_nop 0
	s_nop 0
	v_pk_add_f32 v[234:235], v[234:235], v[146:147]
	v_pk_add_f32 v[238:239], v[238:239], v[146:147]
	v_pk_add_f32 v[236:237], v[236:237], v[146:147]
	v_pk_add_f32 v[240:241], v[240:241], v[146:147]
	v_rcp_f32_e32 v234, v234
	v_rcp_f32_e32 v238, v238
	v_rcp_f32_e32 v235, v235
	v_rcp_f32_e32 v239, v239
	v_rcp_f32_e32 v236, v236
	v_rcp_f32_e32 v240, v240
	v_rcp_f32_e32 v237, v237
	v_rcp_f32_e32 v241, v241
	s_nop 0
	s_nop 0
	v_pk_mul_f32 v[234:235], v[234:235], v[226:227]
	v_pk_mul_f32 v[238:239], v[238:239], v[230:231]
	v_pk_mul_f32 v[236:237], v[236:237], v[228:229]
	v_pk_mul_f32 v[240:241], v[240:241], v[232:233]
	v_pk_mul_f32 v[234:235], v[100:101], v[234:235]
	v_pk_mul_f32 v[238:239], v[88:89], v[238:239]
	v_pk_mul_f32 v[236:237], v[102:103], v[236:237]
	v_pk_mul_f32 v[240:241], v[90:91], v[240:241]
	v_cndmask_b32_e32 v100, v234, v100, vcc
	v_cndmask_b32_e32 v88, v238, v88, vcc
	v_cndmask_b32_e32 v101, v235, v101, vcc
	v_cndmask_b32_e32 v89, v239, v89, vcc
	v_cndmask_b32_e32 v102, v236, v102, vcc
	v_cndmask_b32_e32 v90, v240, v90, vcc
	v_cndmask_b32_e32 v103, v237, v103, vcc
	v_cndmask_b32_e32 v91, v241, v91, vcc
	v_cvt_pk_bf16_f32 v100, v100, v101
	v_cvt_pk_bf16_f32 v101, v102, v103
	v_cvt_pk_bf16_f32 v102, v88, v89
	v_cvt_pk_bf16_f32 v103, v90, v91
	v_mov_b32_e32 v242, v225
	global_store_dwordx4 v242, v[100:103], s[46:47]
	v_pk_mul_f32 v[60:61], v[60:61], v[162:163] op_sel_hi:[1,0]
	v_pk_mul_f32 v[62:63], v[62:63], v[162:163] op_sel_hi:[1,0]
	v_pk_mul_f32 v[36:37], v[36:37], v[162:163] op_sel_hi:[1,0]
	v_pk_mul_f32 v[38:39], v[38:39], v[162:163] op_sel_hi:[1,0]
	v_pk_mul_f32 v[56:57], v[56:57], v[162:163] op_sel_hi:[1,0]
	v_pk_mul_f32 v[58:59], v[58:59], v[162:163] op_sel_hi:[1,0]
	v_pk_mul_f32 v[24:25], v[24:25], v[162:163] op_sel_hi:[1,0]
	v_pk_mul_f32 v[26:27], v[26:27], v[162:163] op_sel_hi:[1,0]
	v_pk_mul_f32 v[44:45], v[44:45], v[164:165] op_sel_hi:[1,0]
	v_pk_mul_f32 v[46:47], v[46:47], v[164:165] op_sel_hi:[1,0]
	v_pk_mul_f32 v[20:21], v[20:21], v[164:165] op_sel_hi:[1,0]
	v_pk_mul_f32 v[22:23], v[22:23], v[164:165] op_sel_hi:[1,0]
	v_pk_mul_f32 v[32:33], v[32:33], v[164:165] op_sel_hi:[1,0]
	v_pk_mul_f32 v[34:35], v[34:35], v[164:165] op_sel_hi:[1,0]
	v_pk_mul_f32 v[12:13], v[12:13], v[164:165] op_sel_hi:[1,0]
	v_pk_mul_f32 v[14:15], v[14:15], v[164:165] op_sel_hi:[1,0]
	v_pk_mul_f32 v[40:41], v[40:41], v[174:175] op_sel_hi:[1,0]
	v_pk_mul_f32 v[42:43], v[42:43], v[174:175] op_sel_hi:[1,0]
	v_pk_mul_f32 v[16:17], v[16:17], v[174:175] op_sel_hi:[1,0]
	v_pk_mul_f32 v[18:19], v[18:19], v[174:175] op_sel_hi:[1,0]
	v_pk_mul_f32 v[28:29], v[28:29], v[174:175] op_sel_hi:[1,0]
	v_pk_mul_f32 v[30:31], v[30:31], v[174:175] op_sel_hi:[1,0]
	v_pk_mul_f32 v[4:5], v[4:5], v[174:175] op_sel_hi:[1,0]
	v_pk_mul_f32 v[6:7], v[6:7], v[174:175] op_sel_hi:[1,0]
	v_pk_mul_f32 v[52:53], v[52:53], v[176:177] op_sel_hi:[1,0]
	v_pk_mul_f32 v[54:55], v[54:55], v[176:177] op_sel_hi:[1,0]
	v_pk_mul_f32 v[8:9], v[8:9], v[176:177] op_sel_hi:[1,0]
	v_pk_mul_f32 v[10:11], v[10:11], v[176:177] op_sel_hi:[1,0]
	v_pk_mul_f32 v[48:49], v[48:49], v[176:177] op_sel_hi:[1,0]
	v_pk_mul_f32 v[50:51], v[50:51], v[176:177] op_sel_hi:[1,0]
	v_pk_mul_f32 v[0:1], v[0:1], v[176:177] op_sel_hi:[1,0]
	v_pk_mul_f32 v[2:3], v[2:3], v[176:177] op_sel_hi:[1,0]
	v_cmp_gt_u32_e32 vcc, 2, v157
	v_cvt_pk_bf16_f32 v214, v60, v61
	v_cvt_pk_bf16_f32 v215, v62, v63
	v_cvt_pk_bf16_f32 v216, v56, v57
	v_cvt_pk_bf16_f32 v217, v58, v59
	v_cvt_pk_bf16_f32 v218, v52, v53
	v_cvt_pk_bf16_f32 v219, v54, v55
	v_cvt_pk_bf16_f32 v220, v48, v49
	v_cvt_pk_bf16_f32 v221, v50, v51
	v_cndmask_b32_e32 v214, v218, v214, vcc
	v_cndmask_b32_e32 v215, v219, v215, vcc
	v_cndmask_b32_e32 v216, v220, v216, vcc
	v_cndmask_b32_e32 v217, v221, v217, vcc
	v_and_b32_e32 v223, 3, v222
	v_add3_u32 v223, s22, v223, 8
	v_mul_u32_u24_e32 v223, 0x1600, v223
	v_lshl_add_u32 v224, v158, 1, v223
	v_cmp_gt_u32_e64 s[10:11], 4, v222
	s_and_saveexec_b64 s[20:21], s[10:11]
	global_store_dwordx4 v224, v[214:217], s[48:49]
	s_mov_b64 exec, s[20:21]
	s_nop 4
	v_pk_fma_f32 v[226:227], v[52:53], v[198:199], v[206:207]
	v_pk_fma_f32 v[230:231], v[48:49], v[202:203], v[210:211]
	v_pk_fma_f32 v[228:229], v[54:55], v[200:201], v[208:209]
	v_pk_fma_f32 v[232:233], v[50:51], v[204:205], v[212:213]
	v_fmac_f32_dpp v226, v52, v190 row_shr:1 row_mask:0xf bank_mask:0xf
	v_fmac_f32_dpp v230, v48, v194 row_shr:1 row_mask:0xf bank_mask:0xf
	v_fmac_f32_dpp v226, v40, v190 row_shl:15 row_mask:0xf bank_mask:0xf
	v_fmac_f32_dpp v230, v28, v194 row_shl:15 row_mask:0xf bank_mask:0xf
	v_fmac_f32_dpp v226, v52, v182 row_shr:2 row_mask:0xf bank_mask:0xf
	v_fmac_f32_dpp v230, v48, v186 row_shr:2 row_mask:0xf bank_mask:0xf
	v_fmac_f32_dpp v226, v40, v182 row_shl:14 row_mask:0xf bank_mask:0xf
	v_fmac_f32_dpp v230, v28, v186 row_shl:14 row_mask:0xf bank_mask:0xf
	v_fmac_f32_dpp v227, v53, v191 row_shr:1 row_mask:0xf bank_mask:0xf
	v_fmac_f32_dpp v231, v49, v195 row_shr:1 row_mask:0xf bank_mask:0xf
	v_fmac_f32_dpp v227, v41, v191 row_shl:15 row_mask:0xf bank_mask:0xf
	v_fmac_f32_dpp v231, v29, v195 row_shl:15 row_mask:0xf bank_mask:0xf
	v_fmac_f32_dpp v227, v53, v183 row_shr:2 row_mask:0xf bank_mask:0xf
	v_fmac_f32_dpp v231, v49, v187 row_shr:2 row_mask:0xf bank_mask:0xf
	v_fmac_f32_dpp v227, v41, v183 row_shl:14 row_mask:0xf bank_mask:0xf
	v_fmac_f32_dpp v231, v29, v187 row_shl:14 row_mask:0xf bank_mask:0xf
	v_fmac_f32_dpp v228, v54, v192 row_shr:1 row_mask:0xf bank_mask:0xf
	v_fmac_f32_dpp v232, v50, v196 row_shr:1 row_mask:0xf bank_mask:0xf
	v_fmac_f32_dpp v228, v42, v192 row_shl:15 row_mask:0xf bank_mask:0xf
	v_fmac_f32_dpp v232, v30, v196 row_shl:15 row_mask:0xf bank_mask:0xf
	v_fmac_f32_dpp v228, v54, v184 row_shr:2 row_mask:0xf bank_mask:0xf
	v_fmac_f32_dpp v232, v50, v188 row_shr:2 row_mask:0xf bank_mask:0xf
	v_fmac_f32_dpp v228, v42, v184 row_shl:14 row_mask:0xf bank_mask:0xf
	v_fmac_f32_dpp v232, v30, v188 row_shl:14 row_mask:0xf bank_mask:0xf
	v_fmac_f32_dpp v229, v55, v193 row_shr:1 row_mask:0xf bank_mask:0xf
	v_fmac_f32_dpp v233, v51, v197 row_shr:1 row_mask:0xf bank_mask:0xf
	v_fmac_f32_dpp v229, v43, v193 row_shl:15 row_mask:0xf bank_mask:0xf
	v_fmac_f32_dpp v233, v31, v197 row_shl:15 row_mask:0xf bank_mask:0xf
	v_fmac_f32_dpp v229, v55, v185 row_shr:2 row_mask:0xf bank_mask:0xf
	v_fmac_f32_dpp v233, v51, v189 row_shr:2 row_mask:0xf bank_mask:0xf
	v_fmac_f32_dpp v229, v43, v185 row_shl:14 row_mask:0xf bank_mask:0xf
	v_fmac_f32_dpp v233, v31, v189 row_shl:14 row_mask:0xf bank_mask:0xf
	v_pk_mul_f32 v[234:235], v[226:227], v[226:227]
	v_pk_mul_f32 v[238:239], v[230:231], v[230:231]
	v_pk_mul_f32 v[236:237], v[228:229], v[228:229]
	v_pk_mul_f32 v[240:241], v[232:233], v[232:233]
	v_pk_fma_f32 v[234:235], v[234:235], v[144:145], v[142:143]
	v_pk_fma_f32 v[238:239], v[238:239], v[144:145], v[142:143]
	v_pk_fma_f32 v[236:237], v[236:237], v[144:145], v[142:143]
	v_pk_fma_f32 v[240:241], v[240:241], v[144:145], v[142:143]
	v_pk_mul_f32 v[234:235], v[234:235], v[226:227]
	v_pk_mul_f32 v[238:239], v[238:239], v[230:231]
	v_pk_mul_f32 v[236:237], v[236:237], v[228:229]
	v_pk_mul_f32 v[240:241], v[240:241], v[232:233]
	v_exp_f32_e32 v234, v234
	v_exp_f32_e32 v238, v238
	v_exp_f32_e32 v235, v235
	v_exp_f32_e32 v239, v239
	v_exp_f32_e32 v236, v236
	v_exp_f32_e32 v240, v240
	v_exp_f32_e32 v237, v237
	v_exp_f32_e32 v241, v241
	s_nop 0
	s_nop 0
	v_pk_add_f32 v[234:235], v[234:235], v[146:147]
	v_pk_add_f32 v[238:239], v[238:239], v[146:147]
	v_pk_add_f32 v[236:237], v[236:237], v[146:147]
	v_pk_add_f32 v[240:241], v[240:241], v[146:147]
	v_rcp_f32_e32 v234, v234
	v_rcp_f32_e32 v238, v238
	v_rcp_f32_e32 v235, v235
	v_rcp_f32_e32 v239, v239
	v_rcp_f32_e32 v236, v236
	v_rcp_f32_e32 v240, v240
	v_rcp_f32_e32 v237, v237
	v_rcp_f32_e32 v241, v241
	s_nop 0
	s_nop 0
	v_pk_mul_f32 v[234:235], v[234:235], v[226:227]
	v_pk_mul_f32 v[238:239], v[238:239], v[230:231]
	v_pk_mul_f32 v[236:237], v[236:237], v[228:229]
	v_pk_mul_f32 v[240:241], v[240:241], v[232:233]
	v_pk_mul_f32 v[8:9], v[8:9], v[234:235]
	v_pk_mul_f32 v[0:1], v[0:1], v[238:239]
	v_pk_mul_f32 v[10:11], v[10:11], v[236:237]
	v_pk_mul_f32 v[2:3], v[2:3], v[240:241]
	v_cvt_pk_bf16_f32 v8, v8, v9
	v_cvt_pk_bf16_f32 v9, v10, v11
	v_cvt_pk_bf16_f32 v10, v0, v1
	v_cvt_pk_bf16_f32 v11, v2, v3
	v_add_u32_e32 v245, 0xf2000, v225
	global_store_dwordx4 v245, v[8:11], s[46:47]
	v_pk_fma_f32 v[226:227], v[40:41], v[198:199], v[206:207]
	v_pk_fma_f32 v[230:231], v[28:29], v[202:203], v[210:211]
	v_pk_fma_f32 v[228:229], v[42:43], v[200:201], v[208:209]
	v_pk_fma_f32 v[232:233], v[30:31], v[204:205], v[212:213]
	v_fmac_f32_dpp v226, v40, v190 row_shr:1 row_mask:0xf bank_mask:0xf
	v_fmac_f32_dpp v230, v28, v194 row_shr:1 row_mask:0xf bank_mask:0xf
	v_fmac_f32_dpp v226, v44, v190 row_shl:15 row_mask:0xf bank_mask:0xf
	v_fmac_f32_dpp v230, v32, v194 row_shl:15 row_mask:0xf bank_mask:0xf
	v_fmac_f32_dpp v226, v40, v182 row_shr:2 row_mask:0xf bank_mask:0xf
	v_fmac_f32_dpp v230, v28, v186 row_shr:2 row_mask:0xf bank_mask:0xf
	v_fmac_f32_dpp v226, v44, v182 row_shl:14 row_mask:0xf bank_mask:0xf
	v_fmac_f32_dpp v230, v32, v186 row_shl:14 row_mask:0xf bank_mask:0xf
	v_fmac_f32_dpp v227, v41, v191 row_shr:1 row_mask:0xf bank_mask:0xf
	v_fmac_f32_dpp v231, v29, v195 row_shr:1 row_mask:0xf bank_mask:0xf
	v_fmac_f32_dpp v227, v45, v191 row_shl:15 row_mask:0xf bank_mask:0xf
	v_fmac_f32_dpp v231, v33, v195 row_shl:15 row_mask:0xf bank_mask:0xf
	v_fmac_f32_dpp v227, v41, v183 row_shr:2 row_mask:0xf bank_mask:0xf
	v_fmac_f32_dpp v231, v29, v187 row_shr:2 row_mask:0xf bank_mask:0xf
	v_fmac_f32_dpp v227, v45, v183 row_shl:14 row_mask:0xf bank_mask:0xf
	v_fmac_f32_dpp v231, v33, v187 row_shl:14 row_mask:0xf bank_mask:0xf
	v_fmac_f32_dpp v228, v42, v192 row_shr:1 row_mask:0xf bank_mask:0xf
	v_fmac_f32_dpp v232, v30, v196 row_shr:1 row_mask:0xf bank_mask:0xf
	v_fmac_f32_dpp v228, v46, v192 row_shl:15 row_mask:0xf bank_mask:0xf
	v_fmac_f32_dpp v232, v34, v196 row_shl:15 row_mask:0xf bank_mask:0xf
	v_fmac_f32_dpp v228, v42, v184 row_shr:2 row_mask:0xf bank_mask:0xf
	v_fmac_f32_dpp v232, v30, v188 row_shr:2 row_mask:0xf bank_mask:0xf
	v_fmac_f32_dpp v228, v46, v184 row_shl:14 row_mask:0xf bank_mask:0xf
	v_fmac_f32_dpp v232, v34, v188 row_shl:14 row_mask:0xf bank_mask:0xf
	v_fmac_f32_dpp v229, v43, v193 row_shr:1 row_mask:0xf bank_mask:0xf
	v_fmac_f32_dpp v233, v31, v197 row_shr:1 row_mask:0xf bank_mask:0xf
	v_fmac_f32_dpp v229, v47, v193 row_shl:15 row_mask:0xf bank_mask:0xf
	v_fmac_f32_dpp v233, v35, v197 row_shl:15 row_mask:0xf bank_mask:0xf
	v_fmac_f32_dpp v229, v43, v185 row_shr:2 row_mask:0xf bank_mask:0xf
	v_fmac_f32_dpp v233, v31, v189 row_shr:2 row_mask:0xf bank_mask:0xf
	v_fmac_f32_dpp v229, v47, v185 row_shl:14 row_mask:0xf bank_mask:0xf
	v_fmac_f32_dpp v233, v35, v189 row_shl:14 row_mask:0xf bank_mask:0xf
	v_pk_mul_f32 v[234:235], v[226:227], v[226:227]
	v_pk_mul_f32 v[238:239], v[230:231], v[230:231]
	v_pk_mul_f32 v[236:237], v[228:229], v[228:229]
	v_pk_mul_f32 v[240:241], v[232:233], v[232:233]
	v_pk_fma_f32 v[234:235], v[234:235], v[144:145], v[142:143]
	v_pk_fma_f32 v[238:239], v[238:239], v[144:145], v[142:143]
	v_pk_fma_f32 v[236:237], v[236:237], v[144:145], v[142:143]
	v_pk_fma_f32 v[240:241], v[240:241], v[144:145], v[142:143]
	v_pk_mul_f32 v[234:235], v[234:235], v[226:227]
	v_pk_mul_f32 v[238:239], v[238:239], v[230:231]
	v_pk_mul_f32 v[236:237], v[236:237], v[228:229]
	v_pk_mul_f32 v[240:241], v[240:241], v[232:233]
	v_exp_f32_e32 v234, v234
	v_exp_f32_e32 v238, v238
	v_exp_f32_e32 v235, v235
	v_exp_f32_e32 v239, v239
	v_exp_f32_e32 v236, v236
	v_exp_f32_e32 v240, v240
	v_exp_f32_e32 v237, v237
	v_exp_f32_e32 v241, v241
	s_nop 0
	s_nop 0
	v_pk_add_f32 v[234:235], v[234:235], v[146:147]
	v_pk_add_f32 v[238:239], v[238:239], v[146:147]
	v_pk_add_f32 v[236:237], v[236:237], v[146:147]
	v_pk_add_f32 v[240:241], v[240:241], v[146:147]
	v_rcp_f32_e32 v234, v234
	v_rcp_f32_e32 v238, v238
	v_rcp_f32_e32 v235, v235
	v_rcp_f32_e32 v239, v239
	v_rcp_f32_e32 v236, v236
	v_rcp_f32_e32 v240, v240
	v_rcp_f32_e32 v237, v237
	v_rcp_f32_e32 v241, v241
	s_nop 0
	s_nop 0
	v_pk_mul_f32 v[234:235], v[234:235], v[226:227]
	v_pk_mul_f32 v[238:239], v[238:239], v[230:231]
	v_pk_mul_f32 v[236:237], v[236:237], v[228:229]
	v_pk_mul_f32 v[240:241], v[240:241], v[232:233]
	v_pk_mul_f32 v[16:17], v[16:17], v[234:235]
	v_pk_mul_f32 v[4:5], v[4:5], v[238:239]
	v_pk_mul_f32 v[18:19], v[18:19], v[236:237]
	v_pk_mul_f32 v[6:7], v[6:7], v[240:241]
	v_cvt_pk_bf16_f32 v16, v16, v17
	v_cvt_pk_bf16_f32 v17, v18, v19
	v_cvt_pk_bf16_f32 v18, v4, v5
	v_cvt_pk_bf16_f32 v19, v6, v7
	v_add_u32_e32 v244, 0xdc000, v225
	global_store_dwordx4 v244, v[16:19], s[46:47]
	v_pk_fma_f32 v[226:227], v[44:45], v[198:199], v[206:207]
	v_pk_fma_f32 v[230:231], v[32:33], v[202:203], v[210:211]
	v_pk_fma_f32 v[228:229], v[46:47], v[200:201], v[208:209]
	v_pk_fma_f32 v[232:233], v[34:35], v[204:205], v[212:213]
	v_fmac_f32_dpp v226, v44, v190 row_shr:1 row_mask:0xf bank_mask:0xf
	v_fmac_f32_dpp v230, v32, v194 row_shr:1 row_mask:0xf bank_mask:0xf
	v_fmac_f32_dpp v226, v60, v190 row_shl:15 row_mask:0xf bank_mask:0xf
	v_fmac_f32_dpp v230, v56, v194 row_shl:15 row_mask:0xf bank_mask:0xf
	v_fmac_f32_dpp v226, v44, v182 row_shr:2 row_mask:0xf bank_mask:0xf
	v_fmac_f32_dpp v230, v32, v186 row_shr:2 row_mask:0xf bank_mask:0xf
	v_fmac_f32_dpp v226, v60, v182 row_shl:14 row_mask:0xf bank_mask:0xf
	v_fmac_f32_dpp v230, v56, v186 row_shl:14 row_mask:0xf bank_mask:0xf
	v_fmac_f32_dpp v227, v45, v191 row_shr:1 row_mask:0xf bank_mask:0xf
	v_fmac_f32_dpp v231, v33, v195 row_shr:1 row_mask:0xf bank_mask:0xf
	v_fmac_f32_dpp v227, v61, v191 row_shl:15 row_mask:0xf bank_mask:0xf
	v_fmac_f32_dpp v231, v57, v195 row_shl:15 row_mask:0xf bank_mask:0xf
	v_fmac_f32_dpp v227, v45, v183 row_shr:2 row_mask:0xf bank_mask:0xf
	v_fmac_f32_dpp v231, v33, v187 row_shr:2 row_mask:0xf bank_mask:0xf
	v_fmac_f32_dpp v227, v61, v183 row_shl:14 row_mask:0xf bank_mask:0xf
	v_fmac_f32_dpp v231, v57, v187 row_shl:14 row_mask:0xf bank_mask:0xf
	v_fmac_f32_dpp v228, v46, v192 row_shr:1 row_mask:0xf bank_mask:0xf
	v_fmac_f32_dpp v232, v34, v196 row_shr:1 row_mask:0xf bank_mask:0xf
	v_fmac_f32_dpp v228, v62, v192 row_shl:15 row_mask:0xf bank_mask:0xf
	v_fmac_f32_dpp v232, v58, v196 row_shl:15 row_mask:0xf bank_mask:0xf
	v_fmac_f32_dpp v228, v46, v184 row_shr:2 row_mask:0xf bank_mask:0xf
	v_fmac_f32_dpp v232, v34, v188 row_shr:2 row_mask:0xf bank_mask:0xf
	v_fmac_f32_dpp v228, v62, v184 row_shl:14 row_mask:0xf bank_mask:0xf
	v_fmac_f32_dpp v232, v58, v188 row_shl:14 row_mask:0xf bank_mask:0xf
	v_fmac_f32_dpp v229, v47, v193 row_shr:1 row_mask:0xf bank_mask:0xf
	v_fmac_f32_dpp v233, v35, v197 row_shr:1 row_mask:0xf bank_mask:0xf
	v_fmac_f32_dpp v229, v63, v193 row_shl:15 row_mask:0xf bank_mask:0xf
	v_fmac_f32_dpp v233, v59, v197 row_shl:15 row_mask:0xf bank_mask:0xf
	v_fmac_f32_dpp v229, v47, v185 row_shr:2 row_mask:0xf bank_mask:0xf
	v_fmac_f32_dpp v233, v35, v189 row_shr:2 row_mask:0xf bank_mask:0xf
	v_fmac_f32_dpp v229, v63, v185 row_shl:14 row_mask:0xf bank_mask:0xf
	v_fmac_f32_dpp v233, v59, v189 row_shl:14 row_mask:0xf bank_mask:0xf
	v_pk_mul_f32 v[234:235], v[226:227], v[226:227]
	v_pk_mul_f32 v[238:239], v[230:231], v[230:231]
	v_pk_mul_f32 v[236:237], v[228:229], v[228:229]
	v_pk_mul_f32 v[240:241], v[232:233], v[232:233]
	v_pk_fma_f32 v[234:235], v[234:235], v[144:145], v[142:143]
	v_pk_fma_f32 v[238:239], v[238:239], v[144:145], v[142:143]
	v_pk_fma_f32 v[236:237], v[236:237], v[144:145], v[142:143]
	v_pk_fma_f32 v[240:241], v[240:241], v[144:145], v[142:143]
	v_pk_mul_f32 v[234:235], v[234:235], v[226:227]
	v_pk_mul_f32 v[238:239], v[238:239], v[230:231]
	v_pk_mul_f32 v[236:237], v[236:237], v[228:229]
	v_pk_mul_f32 v[240:241], v[240:241], v[232:233]
	v_exp_f32_e32 v234, v234
	v_exp_f32_e32 v238, v238
	v_exp_f32_e32 v235, v235
	v_exp_f32_e32 v239, v239
	v_exp_f32_e32 v236, v236
	v_exp_f32_e32 v240, v240
	v_exp_f32_e32 v237, v237
	v_exp_f32_e32 v241, v241
	s_nop 0
	s_nop 0
	v_pk_add_f32 v[234:235], v[234:235], v[146:147]
	v_pk_add_f32 v[238:239], v[238:239], v[146:147]
	v_pk_add_f32 v[236:237], v[236:237], v[146:147]
	v_pk_add_f32 v[240:241], v[240:241], v[146:147]
	v_rcp_f32_e32 v234, v234
	v_rcp_f32_e32 v238, v238
	v_rcp_f32_e32 v235, v235
	v_rcp_f32_e32 v239, v239
	v_rcp_f32_e32 v236, v236
	v_rcp_f32_e32 v240, v240
	v_rcp_f32_e32 v237, v237
	v_rcp_f32_e32 v241, v241
	s_nop 0
	s_nop 0
	v_pk_mul_f32 v[234:235], v[234:235], v[226:227]
	v_pk_mul_f32 v[238:239], v[238:239], v[230:231]
	v_pk_mul_f32 v[236:237], v[236:237], v[228:229]
	v_pk_mul_f32 v[240:241], v[240:241], v[232:233]
	v_pk_mul_f32 v[20:21], v[20:21], v[234:235]
	v_pk_mul_f32 v[12:13], v[12:13], v[238:239]
	v_pk_mul_f32 v[22:23], v[22:23], v[236:237]
	v_pk_mul_f32 v[14:15], v[14:15], v[240:241]
	v_cvt_pk_bf16_f32 v20, v20, v21
	v_cvt_pk_bf16_f32 v21, v22, v23
	v_cvt_pk_bf16_f32 v22, v12, v13
	v_cvt_pk_bf16_f32 v23, v14, v15
	v_add_u32_e32 v243, 0xc6000, v225
	global_store_dwordx4 v243, v[20:23], s[46:47]
	v_pk_fma_f32 v[226:227], v[60:61], v[198:199], v[206:207]
	v_pk_fma_f32 v[230:231], v[56:57], v[202:203], v[210:211]
	v_pk_fma_f32 v[228:229], v[62:63], v[200:201], v[208:209]
	v_pk_fma_f32 v[232:233], v[58:59], v[204:205], v[212:213]
	v_fmac_f32_dpp v226, v60, v190 row_shr:1 row_mask:0xf bank_mask:0xf
	v_fmac_f32_dpp v230, v56, v194 row_shr:1 row_mask:0xf bank_mask:0xf
	v_fmac_f32_dpp v226, v60, v182 row_shr:2 row_mask:0xf bank_mask:0xf
	v_fmac_f32_dpp v230, v56, v186 row_shr:2 row_mask:0xf bank_mask:0xf
	v_fmac_f32_dpp v227, v61, v191 row_shr:1 row_mask:0xf bank_mask:0xf
	v_fmac_f32_dpp v231, v57, v195 row_shr:1 row_mask:0xf bank_mask:0xf
	v_fmac_f32_dpp v227, v61, v183 row_shr:2 row_mask:0xf bank_mask:0xf
	v_fmac_f32_dpp v231, v57, v187 row_shr:2 row_mask:0xf bank_mask:0xf
	v_fmac_f32_dpp v228, v62, v192 row_shr:1 row_mask:0xf bank_mask:0xf
	v_fmac_f32_dpp v232, v58, v196 row_shr:1 row_mask:0xf bank_mask:0xf
	v_fmac_f32_dpp v228, v62, v184 row_shr:2 row_mask:0xf bank_mask:0xf
	v_fmac_f32_dpp v232, v58, v188 row_shr:2 row_mask:0xf bank_mask:0xf
	v_fmac_f32_dpp v229, v63, v193 row_shr:1 row_mask:0xf bank_mask:0xf
	v_fmac_f32_dpp v233, v59, v197 row_shr:1 row_mask:0xf bank_mask:0xf
	v_fmac_f32_dpp v229, v63, v185 row_shr:2 row_mask:0xf bank_mask:0xf
	v_fmac_f32_dpp v233, v59, v189 row_shr:2 row_mask:0xf bank_mask:0xf
	v_pk_mul_f32 v[234:235], v[226:227], v[226:227]
	v_pk_mul_f32 v[238:239], v[230:231], v[230:231]
	v_pk_mul_f32 v[236:237], v[228:229], v[228:229]
	v_pk_mul_f32 v[240:241], v[232:233], v[232:233]
	v_pk_fma_f32 v[234:235], v[234:235], v[144:145], v[142:143]
	v_pk_fma_f32 v[238:239], v[238:239], v[144:145], v[142:143]
	v_pk_fma_f32 v[236:237], v[236:237], v[144:145], v[142:143]
	v_pk_fma_f32 v[240:241], v[240:241], v[144:145], v[142:143]
	v_pk_mul_f32 v[234:235], v[234:235], v[226:227]
	v_pk_mul_f32 v[238:239], v[238:239], v[230:231]
	v_pk_mul_f32 v[236:237], v[236:237], v[228:229]
	v_pk_mul_f32 v[240:241], v[240:241], v[232:233]
	v_exp_f32_e32 v234, v234
	v_exp_f32_e32 v238, v238
	v_exp_f32_e32 v235, v235
	v_exp_f32_e32 v239, v239
	v_exp_f32_e32 v236, v236
	v_exp_f32_e32 v240, v240
	v_exp_f32_e32 v237, v237
	v_exp_f32_e32 v241, v241
	s_nop 0
	s_nop 0
	v_pk_add_f32 v[234:235], v[234:235], v[146:147]
	v_pk_add_f32 v[238:239], v[238:239], v[146:147]
	v_pk_add_f32 v[236:237], v[236:237], v[146:147]
	v_pk_add_f32 v[240:241], v[240:241], v[146:147]
	v_rcp_f32_e32 v234, v234
	v_rcp_f32_e32 v238, v238
	v_rcp_f32_e32 v235, v235
	v_rcp_f32_e32 v239, v239
	v_rcp_f32_e32 v236, v236
	v_rcp_f32_e32 v240, v240
	v_rcp_f32_e32 v237, v237
	v_rcp_f32_e32 v241, v241
	s_nop 0
	s_nop 0
	v_pk_mul_f32 v[234:235], v[234:235], v[226:227]
	v_pk_mul_f32 v[238:239], v[238:239], v[230:231]
	v_pk_mul_f32 v[236:237], v[236:237], v[228:229]
	v_pk_mul_f32 v[240:241], v[240:241], v[232:233]
	v_pk_mul_f32 v[234:235], v[36:37], v[234:235]
	v_pk_mul_f32 v[238:239], v[24:25], v[238:239]
	v_pk_mul_f32 v[236:237], v[38:39], v[236:237]
	v_pk_mul_f32 v[240:241], v[26:27], v[240:241]
	v_cndmask_b32_e32 v36, v234, v36, vcc
	v_cndmask_b32_e32 v24, v238, v24, vcc
	v_cndmask_b32_e32 v37, v235, v37, vcc
	v_cndmask_b32_e32 v25, v239, v25, vcc
	v_cndmask_b32_e32 v38, v236, v38, vcc
	v_cndmask_b32_e32 v26, v240, v26, vcc
	v_cndmask_b32_e32 v39, v237, v39, vcc
	v_cndmask_b32_e32 v27, v241, v27, vcc
	v_cvt_pk_bf16_f32 v36, v36, v37
	v_cvt_pk_bf16_f32 v37, v38, v39
	v_cvt_pk_bf16_f32 v38, v24, v25
	v_cvt_pk_bf16_f32 v39, v26, v27
	v_add_u32_e32 v242, 0xb0000, v225
	global_store_dwordx4 v242, v[36:39], s[46:47]
	s_andn2_b64 vcc, exec, s[0:1]
	s_mov_b64 s[0:1], -1
	s_cbranch_vccnz .LBB0_1511
	s_andn2_b64 vcc, exec, s[42:43]
	s_cbranch_vccnz .LBB0_1510
	s_barrier
	s_branch .LBB0_1510
